# combo12
# speedup vs baseline: 1.0157x; 1.0012x over previous
.LBB0_281:
	s_andn2_b64 vcc, exec, s[30:31]
	s_cbranch_vccnz .LBB0_283
	v_readlane_b32 s4, v254, 24
	s_add_u32 s4, s4, s42
	v_readlane_b32 s5, v254, 25
	s_addc_u32 s5, s5, s43
	v_lshlrev_b32_e32 v0, 2, v137
	v_lshl_add_u64 v[140:141], s[4:5], 0, v[0:1]
	v_ashrrev_i32_e32 v133, 31, v132
	v_lshl_add_u64 v[140:141], v[132:133], 2, v[140:141]
	global_store_dwordx4 v[140:141], v[126:129], off sc1 nt

.LBB0_288:
	s_andn2_b64 vcc, exec, s[4:5]
	s_cbranch_vccnz .LBB0_292
	v_cmp_gt_i32_e32 vcc, 32, v132
	s_and_saveexec_b64 s[4:5], vcc
	s_cbranch_execz .LBB0_291
	v_ashrrev_i32_e32 v133, 31, v132
	v_lshl_add_u64 v[140:141], v[132:133], 2, v[138:139]
	global_store_dwordx4 v[140:141], v[126:129], off sc1 nt

.LBB0_308:
	s_andn2_b64 vcc, exec, s[8:9]
	s_cbranch_vccnz .LBB0_312
	s_andn2_b64 vcc, exec, s[30:31]
	s_cbranch_vccnz .LBB0_311
	v_readlane_b32 s8, v254, 24
	s_add_u32 s8, s8, s42
	v_readlane_b32 s9, v254, 25
	s_addc_u32 s9, s9, s43
	v_lshlrev_b32_e32 v0, 2, v137
	s_ashr_i32 s39, s38, 31
	v_ashrrev_i32_e32 v131, 31, v130
	v_lshl_add_u64 v[126:127], s[8:9], 0, v[0:1]
	v_lshl_add_u64 v[128:129], v[130:131], 0, s[38:39]
	v_lshl_add_u64 v[126:127], v[128:129], 2, v[126:127]
	global_store_dwordx4 v[126:127], v[122:125], off offset:64 sc1 nt

.LBB0_316:
	s_andn2_b64 vcc, exec, s[8:9]
	s_cbranch_vccnz .LBB0_320
	v_cmp_gt_i32_e32 vcc, 32, v144
	s_and_saveexec_b64 s[8:9], vcc
	s_cbranch_execz .LBB0_319
	s_ashr_i32 s39, s38, 31
	v_ashrrev_i32_e32 v131, 31, v130
	v_lshl_add_u64 v[126:127], v[130:131], 0, s[38:39]
	v_lshl_add_u64 v[126:127], v[126:127], 2, v[138:139]
	global_store_dwordx4 v[126:127], v[122:125], off offset:64 sc1 nt

.LBB0_334:
	s_andn2_b64 vcc, exec, s[8:9]
	s_cbranch_vccnz .LBB0_338
	s_andn2_b64 vcc, exec, s[30:31]
	s_cbranch_vccnz .LBB0_337
	v_readlane_b32 s8, v254, 24
	s_add_u32 s8, s8, s42
	v_readlane_b32 s9, v254, 25
	s_addc_u32 s9, s9, s43
	v_lshlrev_b32_e32 v0, 2, v137
	s_ashr_i32 s39, s38, 31
	v_ashrrev_i32_e32 v131, 31, v130
	v_lshl_add_u64 v[122:123], s[8:9], 0, v[0:1]
	v_lshl_add_u64 v[124:125], v[130:131], 0, s[38:39]
	v_lshl_add_u64 v[122:123], v[124:125], 2, v[122:123]
	global_store_dwordx4 v[122:123], v[118:121], off offset:128 sc1 nt

.LBB0_342:
	s_andn2_b64 vcc, exec, s[8:9]
	s_cbranch_vccnz .LBB0_346
	v_cmp_gt_i32_e32 vcc, 32, v140
	s_and_saveexec_b64 s[8:9], vcc
	s_cbranch_execz .LBB0_345
	s_ashr_i32 s39, s38, 31
	v_ashrrev_i32_e32 v131, 31, v130
	v_lshl_add_u64 v[122:123], v[130:131], 0, s[38:39]
	v_lshl_add_u64 v[122:123], v[122:123], 2, v[138:139]
	global_store_dwordx4 v[122:123], v[118:121], off offset:128 sc1 nt

.LBB0_360:
	s_andn2_b64 vcc, exec, s[8:9]
	s_cbranch_vccnz .LBB0_364
	s_andn2_b64 vcc, exec, s[30:31]
	s_cbranch_vccnz .LBB0_363
	v_readlane_b32 s8, v254, 24
	s_add_u32 s8, s8, s42
	v_readlane_b32 s9, v254, 25
	s_addc_u32 s9, s9, s43
	v_lshlrev_b32_e32 v0, 2, v137
	s_ashr_i32 s39, s38, 31
	v_ashrrev_i32_e32 v131, 31, v130
	v_lshl_add_u64 v[118:119], s[8:9], 0, v[0:1]
	v_lshl_add_u64 v[120:121], v[130:131], 0, s[38:39]
	v_lshl_add_u64 v[118:119], v[120:121], 2, v[118:119]
	global_store_dwordx4 v[118:119], v[114:117], off offset:192 sc1 nt

.LBB0_368:
	s_andn2_b64 vcc, exec, s[8:9]
	s_cbranch_vccnz .LBB0_372
	v_cmp_gt_i32_e32 vcc, 32, v126
	s_and_saveexec_b64 s[8:9], vcc
	s_cbranch_execz .LBB0_371
	s_ashr_i32 s39, s38, 31
	v_ashrrev_i32_e32 v131, 31, v130
	v_lshl_add_u64 v[118:119], v[130:131], 0, s[38:39]
	v_lshl_add_u64 v[118:119], v[118:119], 2, v[138:139]
	global_store_dwordx4 v[118:119], v[114:117], off offset:192 sc1 nt

.LBB0_390:
	s_andn2_b64 vcc, exec, s[30:31]
	s_cbranch_vccnz .LBB0_392
	v_readlane_b32 s29, v254, 24
	s_add_u32 s68, s29, s42
	v_readlane_b32 s29, v254, 25
	s_addc_u32 s69, s29, s43
	v_lshlrev_b32_e32 v0, 2, v128
	v_lshl_add_u64 v[120:121], s[68:69], 0, v[0:1]
	v_ashrrev_i32_e32 v133, 31, v132
	v_lshl_add_u64 v[120:121], v[132:133], 2, v[120:121]
	global_store_dwordx4 v[120:121], v[110:113], off sc1 nt

.LBB0_397:
	s_andn2_b64 vcc, exec, s[68:69]
	s_cbranch_vccnz .LBB0_401
	v_cmp_gt_i32_e32 vcc, 32, v132
	s_and_saveexec_b64 s[68:69], vcc
	s_cbranch_execz .LBB0_400
	v_ashrrev_i32_e32 v133, 31, v132
	v_lshl_add_u64 v[120:121], v[132:133], 2, v[118:119]
	global_store_dwordx4 v[120:121], v[110:113], off sc1 nt

.LBB0_415:
	s_andn2_b64 vcc, exec, s[68:69]
	s_cbranch_vccnz .LBB0_419
	s_andn2_b64 vcc, exec, s[30:31]
	s_cbranch_vccnz .LBB0_418
	v_readlane_b32 s29, v254, 24
	s_add_u32 s68, s29, s42
	v_readlane_b32 s29, v254, 25
	s_addc_u32 s69, s29, s43
	v_lshlrev_b32_e32 v0, 2, v128
	s_ashr_i32 s39, s38, 31
	v_ashrrev_i32_e32 v131, 31, v130
	v_lshl_add_u64 v[110:111], s[68:69], 0, v[0:1]
	v_lshl_add_u64 v[112:113], v[130:131], 0, s[38:39]
	v_lshl_add_u64 v[110:111], v[112:113], 2, v[110:111]
	global_store_dwordx4 v[110:111], v[106:109], off offset:64 sc1 nt

.LBB0_423:
	s_andn2_b64 vcc, exec, s[68:69]
	s_cbranch_vccnz .LBB0_427
	v_cmp_gt_i32_e32 vcc, 32, v144
	s_and_saveexec_b64 s[68:69], vcc
	s_cbranch_execz .LBB0_426
	s_ashr_i32 s39, s38, 31
	v_ashrrev_i32_e32 v131, 31, v130
	v_lshl_add_u64 v[110:111], v[130:131], 0, s[38:39]
	v_lshl_add_u64 v[110:111], v[110:111], 2, v[118:119]
	global_store_dwordx4 v[110:111], v[106:109], off offset:64 sc1 nt

.LBB0_441:
	s_andn2_b64 vcc, exec, s[68:69]
	s_cbranch_vccnz .LBB0_445
	s_andn2_b64 vcc, exec, s[30:31]
	s_cbranch_vccnz .LBB0_444
	v_readlane_b32 s29, v254, 24
	s_add_u32 s68, s29, s42
	v_readlane_b32 s29, v254, 25
	s_addc_u32 s69, s29, s43
	v_lshlrev_b32_e32 v0, 2, v128
	s_ashr_i32 s39, s38, 31
	v_ashrrev_i32_e32 v131, 31, v130
	v_lshl_add_u64 v[106:107], s[68:69], 0, v[0:1]
	v_lshl_add_u64 v[108:109], v[130:131], 0, s[38:39]
	v_lshl_add_u64 v[106:107], v[108:109], 2, v[106:107]
	global_store_dwordx4 v[106:107], v[102:105], off offset:128 sc1 nt

.LBB0_449:
	s_andn2_b64 vcc, exec, s[68:69]
	s_cbranch_vccnz .LBB0_453
	v_cmp_gt_i32_e32 vcc, 32, v140
	s_and_saveexec_b64 s[68:69], vcc
	s_cbranch_execz .LBB0_452
	s_ashr_i32 s39, s38, 31
	v_ashrrev_i32_e32 v131, 31, v130
	v_lshl_add_u64 v[106:107], v[130:131], 0, s[38:39]
	v_lshl_add_u64 v[106:107], v[106:107], 2, v[118:119]
	global_store_dwordx4 v[106:107], v[102:105], off offset:128 sc1 nt

.LBB0_467:
	s_andn2_b64 vcc, exec, s[68:69]
	s_cbranch_vccnz .LBB0_471
	s_andn2_b64 vcc, exec, s[30:31]
	s_cbranch_vccnz .LBB0_470
	v_readlane_b32 s29, v254, 24
	s_add_u32 s68, s29, s42
	v_readlane_b32 s29, v254, 25
	s_addc_u32 s69, s29, s43
	v_lshlrev_b32_e32 v0, 2, v128
	s_ashr_i32 s39, s38, 31
	v_ashrrev_i32_e32 v131, 31, v130
	v_lshl_add_u64 v[102:103], s[68:69], 0, v[0:1]
	v_lshl_add_u64 v[104:105], v[130:131], 0, s[38:39]
	v_lshl_add_u64 v[102:103], v[104:105], 2, v[102:103]
	global_store_dwordx4 v[102:103], v[98:101], off offset:192 sc1 nt

.LBB0_475:
	s_andn2_b64 vcc, exec, s[68:69]
	s_cbranch_vccnz .LBB0_479
	v_cmp_gt_i32_e32 vcc, 32, v126
	s_and_saveexec_b64 s[68:69], vcc
	s_cbranch_execz .LBB0_478
	s_ashr_i32 s39, s38, 31
	v_ashrrev_i32_e32 v131, 31, v130
	v_lshl_add_u64 v[102:103], v[130:131], 0, s[38:39]
	v_lshl_add_u64 v[102:103], v[102:103], 2, v[118:119]
	global_store_dwordx4 v[102:103], v[98:101], off offset:192 sc1 nt

.LBB0_511:
	s_andn2_b64 vcc, exec, s[30:31]
	s_cbranch_vccnz .LBB0_513
	v_readlane_b32 s29, v254, 24
	s_add_u32 s68, s29, s42
	v_readlane_b32 s29, v254, 25
	s_addc_u32 s69, s29, s43
	v_lshlrev_b32_e32 v0, 2, v109
	v_lshl_add_u64 v[102:103], s[68:69], 0, v[0:1]
	v_ashrrev_i32_e32 v133, 31, v132
	v_lshl_add_u64 v[102:103], v[132:133], 2, v[102:103]
	global_store_dwordx4 v[102:103], v[94:97], off sc1 nt

.LBB0_518:
	s_andn2_b64 vcc, exec, s[68:69]
	s_cbranch_vccnz .LBB0_522
	v_cmp_gt_i32_e32 vcc, 32, v132
	s_and_saveexec_b64 s[68:69], vcc
	s_cbranch_execz .LBB0_521
	v_ashrrev_i32_e32 v133, 31, v132
	v_lshl_add_u64 v[102:103], v[132:133], 2, v[100:101]
	global_store_dwordx4 v[102:103], v[94:97], off sc1 nt

.LBB0_536:
	s_andn2_b64 vcc, exec, s[68:69]
	s_cbranch_vccnz .LBB0_540
	s_andn2_b64 vcc, exec, s[30:31]
	s_cbranch_vccnz .LBB0_539
	v_readlane_b32 s29, v254, 24
	s_add_u32 s68, s29, s42
	v_readlane_b32 s29, v254, 25
	s_addc_u32 s69, s29, s43
	v_lshlrev_b32_e32 v0, 2, v109
	s_ashr_i32 s39, s38, 31
	v_ashrrev_i32_e32 v131, 31, v130
	v_lshl_add_u64 v[94:95], s[68:69], 0, v[0:1]
	v_lshl_add_u64 v[96:97], v[130:131], 0, s[38:39]
	v_lshl_add_u64 v[94:95], v[96:97], 2, v[94:95]
	global_store_dwordx4 v[94:95], v[90:93], off offset:64 sc1 nt

.LBB0_544:
	s_andn2_b64 vcc, exec, s[68:69]
	s_cbranch_vccnz .LBB0_548
	v_cmp_gt_i32_e32 vcc, 32, v144
	s_and_saveexec_b64 s[68:69], vcc
	s_cbranch_execz .LBB0_547
	s_ashr_i32 s39, s38, 31
	v_ashrrev_i32_e32 v131, 31, v130
	v_lshl_add_u64 v[94:95], v[130:131], 0, s[38:39]
	v_lshl_add_u64 v[94:95], v[94:95], 2, v[100:101]
	global_store_dwordx4 v[94:95], v[90:93], off offset:64 sc1 nt

.LBB0_562:
	s_andn2_b64 vcc, exec, s[68:69]
	s_cbranch_vccnz .LBB0_566
	s_andn2_b64 vcc, exec, s[30:31]
	s_cbranch_vccnz .LBB0_565
	v_readlane_b32 s29, v254, 24
	s_add_u32 s68, s29, s42
	v_readlane_b32 s29, v254, 25
	s_addc_u32 s69, s29, s43
	v_lshlrev_b32_e32 v0, 2, v109
	s_ashr_i32 s39, s38, 31
	v_ashrrev_i32_e32 v131, 31, v130
	v_lshl_add_u64 v[90:91], s[68:69], 0, v[0:1]
	v_lshl_add_u64 v[92:93], v[130:131], 0, s[38:39]
	v_lshl_add_u64 v[90:91], v[92:93], 2, v[90:91]
	global_store_dwordx4 v[90:91], v[86:89], off offset:128 sc1 nt

.LBB0_570:
	s_andn2_b64 vcc, exec, s[68:69]
	s_cbranch_vccnz .LBB0_574
	v_cmp_gt_i32_e32 vcc, 32, v140
	s_and_saveexec_b64 s[68:69], vcc
	s_cbranch_execz .LBB0_573
	s_ashr_i32 s39, s38, 31
	v_ashrrev_i32_e32 v131, 31, v130
	v_lshl_add_u64 v[90:91], v[130:131], 0, s[38:39]
	v_lshl_add_u64 v[90:91], v[90:91], 2, v[100:101]
	global_store_dwordx4 v[90:91], v[86:89], off offset:128 sc1 nt

.LBB0_588:
	s_andn2_b64 vcc, exec, s[68:69]
	s_cbranch_vccnz .LBB0_592
	s_andn2_b64 vcc, exec, s[30:31]
	s_cbranch_vccnz .LBB0_591
	v_readlane_b32 s29, v254, 24
	s_add_u32 s68, s29, s42
	v_readlane_b32 s29, v254, 25
	s_addc_u32 s69, s29, s43
	v_lshlrev_b32_e32 v0, 2, v109
	s_ashr_i32 s39, s38, 31
	v_ashrrev_i32_e32 v131, 31, v130
	v_lshl_add_u64 v[86:87], s[68:69], 0, v[0:1]
	v_lshl_add_u64 v[88:89], v[130:131], 0, s[38:39]
	v_lshl_add_u64 v[86:87], v[88:89], 2, v[86:87]
	global_store_dwordx4 v[86:87], v[82:85], off offset:192 sc1 nt

.LBB0_596:
	s_andn2_b64 vcc, exec, s[68:69]
	s_cbranch_vccnz .LBB0_600
	v_cmp_gt_i32_e32 vcc, 32, v126
	s_and_saveexec_b64 s[68:69], vcc
	s_cbranch_execz .LBB0_599
	s_ashr_i32 s39, s38, 31
	v_ashrrev_i32_e32 v131, 31, v130
	v_lshl_add_u64 v[86:87], v[130:131], 0, s[38:39]
	v_lshl_add_u64 v[86:87], v[86:87], 2, v[100:101]
	global_store_dwordx4 v[86:87], v[82:85], off offset:192 sc1 nt

.LBB0_626:
	s_andn2_b64 vcc, exec, s[30:31]
	s_cbranch_vccnz .LBB0_628
	v_readlane_b32 s29, v254, 24
	s_add_u32 s68, s29, s42
	v_readlane_b32 s29, v254, 25
	s_addc_u32 s69, s29, s43
	v_lshlrev_b32_e32 v0, 2, v92
	v_lshl_add_u64 v[86:87], s[68:69], 0, v[0:1]
	v_ashrrev_i32_e32 v133, 31, v132
	v_lshl_add_u64 v[86:87], v[132:133], 2, v[86:87]
	global_store_dwordx4 v[86:87], v[78:81], off sc1 nt

.LBB0_633:
	s_andn2_b64 vcc, exec, s[68:69]
	s_cbranch_vccnz .LBB0_637
	v_cmp_gt_i32_e32 vcc, 32, v132
	s_and_saveexec_b64 s[68:69], vcc
	s_cbranch_execz .LBB0_636
	v_ashrrev_i32_e32 v133, 31, v132
	v_lshl_add_u64 v[86:87], v[132:133], 2, v[84:85]
	global_store_dwordx4 v[86:87], v[78:81], off sc1 nt

.LBB0_651:
	s_andn2_b64 vcc, exec, s[68:69]
	s_cbranch_vccnz .LBB0_655
	s_andn2_b64 vcc, exec, s[30:31]
	s_cbranch_vccnz .LBB0_654
	v_readlane_b32 s29, v254, 24
	s_add_u32 s68, s29, s42
	v_readlane_b32 s29, v254, 25
	s_addc_u32 s69, s29, s43
	v_lshlrev_b32_e32 v0, 2, v92
	s_ashr_i32 s39, s38, 31
	v_ashrrev_i32_e32 v131, 31, v130
	v_lshl_add_u64 v[78:79], s[68:69], 0, v[0:1]
	v_lshl_add_u64 v[80:81], v[130:131], 0, s[38:39]
	v_lshl_add_u64 v[78:79], v[80:81], 2, v[78:79]
	global_store_dwordx4 v[78:79], v[74:77], off offset:64 sc1 nt

.LBB0_659:
	s_andn2_b64 vcc, exec, s[68:69]
	s_cbranch_vccnz .LBB0_663
	v_cmp_gt_i32_e32 vcc, 32, v144
	s_and_saveexec_b64 s[68:69], vcc
	s_cbranch_execz .LBB0_662
	s_ashr_i32 s39, s38, 31
	v_ashrrev_i32_e32 v131, 31, v130
	v_lshl_add_u64 v[78:79], v[130:131], 0, s[38:39]
	v_lshl_add_u64 v[78:79], v[78:79], 2, v[84:85]
	global_store_dwordx4 v[78:79], v[74:77], off offset:64 sc1 nt

.LBB0_677:
	s_andn2_b64 vcc, exec, s[68:69]
	s_cbranch_vccnz .LBB0_681
	s_andn2_b64 vcc, exec, s[30:31]
	s_cbranch_vccnz .LBB0_680
	v_readlane_b32 s29, v254, 24
	s_add_u32 s68, s29, s42
	v_readlane_b32 s29, v254, 25
	s_addc_u32 s69, s29, s43
	v_lshlrev_b32_e32 v0, 2, v92
	s_ashr_i32 s39, s38, 31
	v_ashrrev_i32_e32 v131, 31, v130
	v_lshl_add_u64 v[74:75], s[68:69], 0, v[0:1]
	v_lshl_add_u64 v[76:77], v[130:131], 0, s[38:39]
	v_lshl_add_u64 v[74:75], v[76:77], 2, v[74:75]
	global_store_dwordx4 v[74:75], v[70:73], off offset:128 sc1 nt

.LBB0_685:
	s_andn2_b64 vcc, exec, s[68:69]
	s_cbranch_vccnz .LBB0_689
	v_cmp_gt_i32_e32 vcc, 32, v140
	s_and_saveexec_b64 s[68:69], vcc
	s_cbranch_execz .LBB0_688
	s_ashr_i32 s39, s38, 31
	v_ashrrev_i32_e32 v131, 31, v130
	v_lshl_add_u64 v[74:75], v[130:131], 0, s[38:39]
	v_lshl_add_u64 v[74:75], v[74:75], 2, v[84:85]
	global_store_dwordx4 v[74:75], v[70:73], off offset:128 sc1 nt

.LBB0_709:
	s_andn2_b64 vcc, exec, s[6:7]
	s_cbranch_vccnz .LBB0_713
	s_andn2_b64 vcc, exec, s[30:31]
	s_cbranch_vccnz .LBB0_712
	v_readlane_b32 s6, v254, 24
	s_add_u32 s6, s6, s42
	v_readlane_b32 s7, v254, 25
	s_addc_u32 s7, s7, s43
	v_lshlrev_b32_e32 v0, 2, v92
	s_ashr_i32 s39, s38, 31
	v_ashrrev_i32_e32 v131, 31, v130
	v_lshl_add_u64 v[70:71], s[6:7], 0, v[0:1]
	v_lshl_add_u64 v[72:73], v[130:131], 0, s[38:39]
	v_lshl_add_u64 v[70:71], v[72:73], 2, v[70:71]
	global_store_dwordx4 v[70:71], v[66:69], off offset:192 sc1 nt

.LBB0_717:
	s_andn2_b64 vcc, exec, s[6:7]
	s_cbranch_vccnz .LBB0_721
	v_cmp_gt_i32_e32 vcc, 32, v126
	s_and_saveexec_b64 s[6:7], vcc
	s_cbranch_execz .LBB0_720
	s_ashr_i32 s39, s38, 31
	v_ashrrev_i32_e32 v131, 31, v130
	v_lshl_add_u64 v[70:71], v[130:131], 0, s[38:39]
	v_lshl_add_u64 v[70:71], v[70:71], 2, v[84:85]
	global_store_dwordx4 v[70:71], v[66:69], off offset:192 sc1 nt

.LBB0_738:
	v_lshlrev_b32_e32 v0, 3, v146
	v_and_b32_e32 v0, 0x78, v0
	v_lshlrev_b32_e32 v0, 1, v0
	v_mad_u64_u32 v[66:67], s[6:7], v70, s30, v[0:1]
	v_lshl_add_u64 v[70:71], v[68:69], 0, v[0:1]
	ds_read_b128 v[66:69], v66
	s_mov_b64 s[28:29], -1
	s_andn2_b64 vcc, exec, s[36:37]
	s_waitcnt lgkmcnt(0)
	global_store_dwordx4 v[70:71], v[66:69], off sc1 nt
	s_nop 1
	v_add_u32_e32 v66, 0x100, v146
	v_ashrrev_i32_e32 v70, 4, v66
	v_cndmask_b32_e64 v67, 0, 1, s[36:37]
	v_add_u32_e32 v66, s13, v70
	v_cmp_ne_u32_e64 s[6:7], 1, v67
	s_cbranch_vccnz .LBB0_740
	v_mov_b64_e32 v[68:69], s[10:11]
	v_mad_i64_i32 v[68:69], s[28:29], v66, s33, v[68:69]
	s_mov_b64 s[28:29], 0

.LBB0_745:
	v_mad_u64_u32 v[66:67], s[28:29], v70, s30, v[0:1]
	v_lshl_add_u64 v[70:71], v[68:69], 0, v[0:1]
	ds_read_b128 v[66:69], v66
	s_mov_b64 s[28:29], -1
	s_and_b64 vcc, exec, s[6:7]
	s_waitcnt lgkmcnt(0)
	global_store_dwordx4 v[70:71], v[66:69], off sc1 nt
	s_nop 1
	v_add_u32_e32 v66, 0x200, v146
	v_ashrrev_i32_e32 v70, 4, v66
	v_add_u32_e32 v66, s13, v70
	s_cbranch_vccnz .LBB0_747
	v_mov_b64_e32 v[68:69], s[10:11]
	v_mad_i64_i32 v[68:69], s[28:29], v66, s33, v[68:69]
	s_mov_b64 s[28:29], 0

.LBB0_752:
	v_mad_u64_u32 v[66:67], s[28:29], v70, s30, v[0:1]
	v_lshl_add_u64 v[70:71], v[68:69], 0, v[0:1]
	ds_read_b128 v[66:69], v66
	s_mov_b64 s[28:29], -1
	s_and_b64 vcc, exec, s[6:7]
	s_waitcnt lgkmcnt(0)
	global_store_dwordx4 v[70:71], v[66:69], off sc1 nt
	s_nop 1
	v_add_u32_e32 v66, 0x300, v146
	v_ashrrev_i32_e32 v70, 4, v66
	v_add_u32_e32 v66, s13, v70
	s_cbranch_vccnz .LBB0_754
	v_mov_b64_e32 v[68:69], s[10:11]
	v_mad_i64_i32 v[68:69], s[28:29], v66, s33, v[68:69]
	s_mov_b64 s[28:29], 0

.LBB0_759:
	v_mad_u64_u32 v[66:67], s[28:29], v70, s30, v[0:1]
	v_lshl_add_u64 v[70:71], v[68:69], 0, v[0:1]
	ds_read_b128 v[66:69], v66
	s_mov_b64 s[28:29], -1
	s_and_b64 vcc, exec, s[6:7]
	s_waitcnt lgkmcnt(0)
	global_store_dwordx4 v[70:71], v[66:69], off sc1 nt
	s_nop 1
	v_add_u32_e32 v66, 0x400, v146
	v_ashrrev_i32_e32 v70, 4, v66
	v_add_u32_e32 v66, s13, v70
	s_cbranch_vccnz .LBB0_761
	v_mov_b64_e32 v[68:69], s[10:11]
	v_mad_i64_i32 v[68:69], s[28:29], v66, s33, v[68:69]
	s_mov_b64 s[28:29], 0

.LBB0_766:
	v_mad_u64_u32 v[66:67], s[28:29], v70, s30, v[0:1]
	v_lshl_add_u64 v[70:71], v[68:69], 0, v[0:1]
	ds_read_b128 v[66:69], v66
	s_mov_b64 s[28:29], -1
	s_and_b64 vcc, exec, s[6:7]
	s_waitcnt lgkmcnt(0)
	global_store_dwordx4 v[70:71], v[66:69], off sc1 nt
	s_nop 1
	v_add_u32_e32 v66, 0x500, v146
	v_ashrrev_i32_e32 v70, 4, v66
	v_add_u32_e32 v66, s13, v70
	s_cbranch_vccnz .LBB0_768
	v_mov_b64_e32 v[68:69], s[10:11]
	v_mad_i64_i32 v[68:69], s[28:29], v66, s33, v[68:69]
	s_mov_b64 s[28:29], 0

.LBB0_773:
	v_mad_u64_u32 v[66:67], s[28:29], v70, s30, v[0:1]
	v_lshl_add_u64 v[70:71], v[68:69], 0, v[0:1]
	ds_read_b128 v[66:69], v66
	s_mov_b64 s[28:29], -1
	s_and_b64 vcc, exec, s[6:7]
	s_waitcnt lgkmcnt(0)
	global_store_dwordx4 v[70:71], v[66:69], off sc1 nt
	s_nop 1
	v_add_u32_e32 v66, 0x600, v146
	v_ashrrev_i32_e32 v70, 4, v66
	v_add_u32_e32 v66, s13, v70
	s_cbranch_vccnz .LBB0_775
	v_mov_b64_e32 v[68:69], s[10:11]
	v_mad_i64_i32 v[68:69], s[28:29], v66, s33, v[68:69]
	s_mov_b64 s[28:29], 0

.LBB0_780:
	v_mad_u64_u32 v[66:67], s[28:29], v70, s30, v[0:1]
	v_lshl_add_u64 v[70:71], v[68:69], 0, v[0:1]
	ds_read_b128 v[66:69], v66
	s_mov_b64 s[28:29], -1
	s_and_b64 vcc, exec, s[6:7]
	s_waitcnt lgkmcnt(0)
	global_store_dwordx4 v[70:71], v[66:69], off sc1 nt
	s_nop 1
	v_add_u32_e32 v66, 0x700, v146
	v_ashrrev_i32_e32 v70, 4, v66
	v_add_u32_e32 v66, s13, v70
	s_cbranch_vccnz .LBB0_782
	v_mov_b64_e32 v[68:69], s[10:11]
	v_mad_i64_i32 v[68:69], s[6:7], v66, s33, v[68:69]
	s_mov_b64 s[28:29], 0

.LBB0_787:
	v_mad_u64_u32 v[66:67], s[4:5], v70, s30, v[0:1]
	v_lshl_add_u64 v[70:71], v[68:69], 0, v[0:1]
	ds_read_b128 v[66:69], v66
	s_waitcnt lgkmcnt(0)
	global_store_dwordx4 v[70:71], v[66:69], off sc1 nt
